# v76 + diff attention: map-B waves take query sub-blocks in reverse order so the two waves of a SIMD balance the diagonal stage
# speedup vs baseline: 1.0120x; 1.0055x over previous
; #define LAS __attribute__((address_space(3)))
; __device__ __forceinline__ void diff_phase(LAS unsigned char* lds, int L) {
;     constexpr int DKS = 18432, DVO = 2 * DKS, DST = DVO + 32768;
;     const KP P = kparams(); const int tid = opaque_tid(), lane = tid & 63, wave = __builtin_amdgcn_readfirstlane(tid >> 6);
;     const int r32 = lane & 31, hi = lane >> 5, map = wave >> 2, wq = wave & 3;
;     const int bx = opaque_bx(), vcu = (bx & 7) * 32 + (bx >> 3), xcd = vcu >> 5, grp = (vcu & 31) >> 3, mi = vcu & 7, eo = L >> 1;
;     unsigned char* ws = P->ws;
;     const bf16* Qb = (const bf16*)(ws + WS_Q); const bf16* Kb = (const bf16*)(ws + WS_K); const bf16* Vb = (const bf16*)(ws + WS_V); bf16* Ob = (bf16*)(ws + WS_O);
;     LAS float* dtab = (LAS float*)(lds + OFF_TAB);
;     const float lam_init = 0.8f - 0.6f * __builtin_amdgcn_exp2f(-0.3f * LOG2E * (float)L);
;     const float s1 = wave_sum(P->lq1[eo * 64 + lane] * P->lk1[eo * 64 + lane]), s2 = wave_sum(P->lq2[eo * 64 + lane] * P->lk2[eo * 64 + lane]);
;     const float lam = __builtin_amdgcn_exp2f(s1 * LOG2E) - __builtin_amdgcn_exp2f(s2 * LOG2E) + lam_init;
;     const int ksub = wave >> 2, krow0 = 32 * (wave & 3) + (lane >> 3);
;     const int klds = ksub * DKS + krow0 * 144 + (lane & 7) * 16;
;     const int vtile = wave >> 2, vdg = wave & 3, vkey0 = 64 * vtile + (lane >> 2);
;     const int vlds = DVO + vtile * 16384 + vdg * 4096 + 16 * lane;
;     for (int ui = 0; ui < 8; ++ui) {
;         const int bh = xcd * 16 + (ui >> 1) * 4 + grp, b = bh >> 3, hj = bh & 7, qblk = (ui & 1) ? mi : 15 - mi;
;         const size_t tokb = (size_t)b * SEQ;
;         const int kgcol = 128 * hj + 64 * ksub + 8 * (lane & 7), vgcol = 128 * hj + 32 * vdg + 8 * (lane & 3);
;         if (!(ui & 1)) {
;             if (tid < 320) { const int d = 207 - tid; float v = 0.f;
;                 if (d < 0) v = -INFINITY;
;                 else if (d < 128) { int bk = d;
;                     if (d >= 16) { bk = 16 + (int)(__builtin_amdgcn_logf((float)d * 0.0625f) * (16.0f / 3.0f)); bk = bk > 31 ? 31 : bk; }
;                     v = (P->rel_bias[bk * 8 + hj] - P->rel_bias[31 * 8 + hj]) * LOG2E; }
;                 dtab[tid] = v; }
;             __syncthreads();
;         }
;         const int q0 = 128 * qblk, NT = qblk + 1, qw0 = q0 + 32 * wq, th = (qw0 + 31) >> 6;
;         bf16x8 qr[4];
.LBB0_175:
	s_or_b64 exec, exec, s[38:39]
	s_andn2_b64 vcc, exec, s[36:37]
	s_mov_b64 s[4:5], -1
	s_waitcnt lgkmcnt(0)
	s_barrier
	s_cbranch_vccnz .LBB0_211
	s_mov_b64 s[8:9], s[60:61]
	v_mov_b32_e32 v3, v197
	s_mov_b32 s4, s57
	s_load_dwordx8 s[12:19], s[8:9], 0x58
	v_and_b32_e32 v6, 63, v3
	s_lshr_b32 s3, s78, 1
	v_lshl_or_b32 v0, s3, 6, v6
	v_mov_b32_e32 v1, v2
	v_lshlrev_b64 v[0:1], 2, v[0:1]
	s_waitcnt lgkmcnt(0)
	v_lshl_add_u64 v[4:5], s[12:13], 0, v[0:1]
	global_load_dword v7, v[4:5], off
	v_lshl_add_u64 v[4:5], s[14:15], 0, v[0:1]
	global_load_dword v8, v[4:5], off
	v_lshl_add_u64 v[4:5], s[16:17], 0, v[0:1]
	v_lshl_add_u64 v[0:1], s[18:19], 0, v[0:1]
	global_load_dword v4, v[4:5], off
	s_load_dwordx2 s[10:11], s[8:9], 0xb0
	global_load_dword v1, v[0:1], off
	v_readfirstlane_b32 s6, v3
	s_lshl_b32 s7, s4, 5
	s_ashr_i32 s21, s4, 3
	s_ashr_i32 s24, s6, 8
	s_bfe_u32 s26, s6, 0x20006
	s_and_b32 s7, s7, 0xe0
	s_bfe_u32 s36, s21, 0x20003
	s_and_b32 s37, s21, 7
	s_waitcnt lgkmcnt(0)
	s_add_u32 s12, s10, 0xa400000
	s_addc_u32 s13, s11, 0
	s_add_u32 s14, s10, 0xe400000
	s_addc_u32 s15, s11, 0
	s_add_u32 s16, s10, 0x12400000
	s_addc_u32 s17, s11, 0
	s_add_u32 s18, s10, 0x16400000
	v_bfe_u32 v11, v3, 3, 3
	v_bfe_u32 v13, v3, 2, 4
	s_addc_u32 s19, s11, 0
	s_lshl_b32 s39, s26, 5
	s_lshl_b32 s20, s24, 6
	v_or_b32_e32 v176, s39, v11
	v_or_b32_e32 v178, s20, v13
	v_sub_u32_e32 v14, 0xcf, v3
	v_cvt_f32_u32_e32 v5, s78
	v_and_b32_e32 v12, 7, v3
	v_cvt_f32_u32_e32 v17, v14
	s_mul_i32 s38, s24, 0x4800
	v_lshlrev_b32_e32 v16, 3, v12
	v_lshl_or_b32 v12, v12, 4, s38
	v_mad_u32_u24 v207, v176, s67, v12
	v_mul_f32_e32 v5, 0xbedd9914, v5
	v_mul_f32_e32 v17, 0x3d800000, v17
	v_exp_f32_e32 v5, v5
	v_log_f32_e32 v17, v17
	s_add_i32 s7, s7, s21
	v_mov_b32_e32 v9, 0x3f4ccccd
	s_ashr_i32 s7, s7, 1
	v_fmamk_f32 v5, v5, 0xbf19999a, v9
	v_mul_f32_e32 v9, 0x40aaaaab, v17
	s_xor_b32 s40, s37, 15
	s_ashr_i32 s21, s20, 31
	s_and_b32 s41, s7, -16
	v_cvt_i32_f32_e32 v9, v9
	s_cmpk_lt_u32 s6, 0x100
	s_cselect_b64 s[22:23], -1, 0
	s_sub_i32 s101, 3, s26
	s_cmp_eq_u32 s24, 1
	s_cselect_b32 s101, s101, s26
	s_lshl_b32 s6, s101, 14
	s_add_i32 s6, s6, 0
	v_lshlrev_b32_e32 v15, 4, v6
	s_cmp_eq_u32 s24, 1
	v_lshl_or_b32 v18, s24, 14, v15
	s_movk_i32 s7, 0xc0
	s_cselect_b64 s[24:25], -1, 0
	s_lshl_b32 s72, s3, 7
	s_movk_i32 s3, 0xff7f
	v_cmp_gt_u32_e32 vcc, s7, v3
	v_lshl_add_u32 v216, v6, 2, s6
	v_and_b32_e32 v177, 31, v3
	v_bfe_u32 v10, v3, 5, 1
	v_lshlrev_b32_e32 v0, 3, v3
	v_and_b32_e32 v181, 24, v0
	v_lshlrev_b32_e32 v211, 4, v10
	s_movk_i32 s5, 0x140
	v_lshlrev_b32_e32 v0, 3, v10
	v_ashrrev_i32_e32 v179, 31, v178
	v_readlane_b32 s1, v254, 0
	v_cmp_gt_i32_e64 s[4:5], s5, v3
	v_lshl_or_b32 v204, s26, 12, v18
	v_or_b32_e32 v205, s20, v16
	v_or_b32_e32 v206, s39, v181
	v_lshl_add_u32 v209, v3, 2, s1
	v_mul_u32_u24_e32 v210, 0x90, v177
	v_lshlrev_b32_e32 v213, 8, v10
	v_and_b32_e32 v214, 0xc0, v15
	v_sub_f32_e32 v217, 1.0, v5
	s_waitcnt vmcnt(0)
	v_mul_f32_e32 v11, v7, v8
	v_lshlrev_b32_e32 v180, 2, v10
	v_lshlrev_b32_e32 v182, 11, v176
	v_mov_b32_dpp v11, v11 quad_perm:[1,0,3,2] row_mask:0xf bank_mask:0xf bound_ctrl:1
	v_fmac_f32_e32 v11, v7, v8
	v_mul_f32_e32 v13, v4, v1
	v_mov_b32_e32 v183, v2
	v_lshlrev_b64 v[184:185], 11, v[178:179]
	v_mov_b32_dpp v13, v13 quad_perm:[1,0,3,2] row_mask:0xf bank_mask:0xf bound_ctrl:1
	v_fmac_f32_e32 v13, v4, v1
	v_add_f32_dpp v1, v11, v11 quad_perm:[2,3,0,1] row_mask:0xf bank_mask:0xf bound_ctrl:1
	s_mov_b32 s42, 0
	v_add_f32_dpp v4, v13, v13 quad_perm:[2,3,0,1] row_mask:0xf bank_mask:0xf bound_ctrl:1
	v_add_f32_dpp v1, v1, v1 row_half_mirror row_mask:0xf bank_mask:0xf bound_ctrl:1
	v_lshlrev_b32_e32 v186, 1, v0
	v_add_f32_dpp v4, v4, v4 row_half_mirror row_mask:0xf bank_mask:0xf bound_ctrl:1
	v_add_f32_dpp v1, v1, v1 row_mirror row_mask:0xf bank_mask:0xf bound_ctrl:1
	ds_swizzle_b32 v7, v1 offset:swizzle(SWAP,16)
	v_add_f32_dpp v4, v4, v4 row_mirror row_mask:0xf bank_mask:0xf bound_ctrl:1
	ds_swizzle_b32 v8, v4 offset:swizzle(SWAP,16)
	s_mov_b32 s43, 0
	s_waitcnt lgkmcnt(1)
	v_add_f32_e32 v1, v1, v7
	v_mov_b32_e32 v7, v1
	s_waitcnt lgkmcnt(0)
	v_add_f32_e32 v4, v4, v8
	v_mov_b32_e32 v8, v1
	v_mov_b32_e32 v11, v4
	v_mov_b32_e32 v12, v4
	v_permlane32_swap_b32_e32 v7, v8
	s_nop 0
	v_permlane32_swap_b32_e32 v11, v12
	v_xor_b32_e32 v7, v7, v8
	v_xor_b32_e32 v8, v11, v12
	v_xor_b32_e32 v7, v7, v1
	v_xor_b32_e32 v8, v8, v4
	v_add_f32_e32 v1, v1, v7
	v_add_f32_e32 v4, v4, v8
	v_mul_f32_e32 v1, 0x3fb8aa3b, v1
	v_mul_f32_e32 v4, 0x3fb8aa3b, v4
	v_exp_f32_e32 v1, v1
	v_exp_f32_e32 v4, v4
	v_min_i32_e32 v7, 15, v9
	v_sub_f32_e32 v1, v1, v4
	v_add_f32_e32 v1, v5, v1
	v_cndmask_b32_e64 v215, v1, 1.0, s[22:23]
	v_add_u32_e32 v1, 0xffffff30, v3
	v_add_u32_e32 v4, 16, v7
	v_cmp_lt_u32_e64 s[6:7], s3, v1
	s_movk_i32 s3, 0xcf
	v_cndmask_b32_e32 v4, v14, v4, vcc
	v_cmp_lt_i32_e32 vcc, s3, v3
	s_lshl_b32 s3, s36, 7
	s_add_i32 s27, s3, s20
	s_or_b32 s3, s3, s39
	s_lshl_b32 s39, s101, 5
	v_lshlrev_b32_e32 v1, 2, v177
	v_or_b32_e32 v220, s3, v181
	v_sub_u32_e32 v1, v211, v1
	s_lshl_b32 s3, s101, 7
	v_lshlrev_b32_e32 v208, 3, v4
	v_lshlrev_b32_e32 v4, 1, v3
	v_subrev_u32_e32 v1, s3, v1
	v_and_b32_e32 v212, 32, v4
	v_cndmask_b32_e32 v218, 0, v249, vcc
	v_or_b32_e32 v219, s27, v16
	v_add_u32_e32 v221, 0, v1
	s_lshl_b64 s[26:27], s[72:73], 2
	s_load_dwordx2 s[44:45], s[8:9], 0x78
	v_cmp_gt_u32_e32 vcc, 0x80, v197
	s_waitcnt lgkmcnt(0)
	s_add_u32 s44, s44, s26
	s_addc_u32 s45, s45, s27
	s_and_saveexec_b64 s[46:47], vcc
	v_lshlrev_b32_e32 v0, 2, v197
	global_load_dword v1, v0, s[44:45]
	v_add_u32_e32 v0, 0x22580, v0
	s_waitcnt vmcnt(0)
	ds_write_b32 v0, v1
	s_or_b64 exec, exec, s[46:47]
	s_mov_b32 s100, 0
	s_branch .LBB0_178
